# v068 + hand-written bf16 in-projection epilogue (no wasted sigmoid) writing CH/BG with padded 4224B rows; short gated conv reads them
# speedup vs baseline: 1.0071x; 1.0017x over previous
; __device__ __forceinline__ const char* unitA(const Gemm& g, const Unit& u) { return (const char*)(g.A + (size_t)(u.z / g.zdiv) * g.sAhi + (size_t)(u.z % g.zdiv) * g.sAlo + (size_t)u.pm * BM * g.lda); }
; __device__ __forceinline__ const char* unitB(const Gemm& g, const Unit& u) { return (const char*)(g.Bt + (size_t)(u.z / g.zdiv) * g.sBhi + (size_t)(u.z % g.zdiv) * g.sBlo + (size_t)(u.pm / g.bdiv) * g.sBpm + (size_t)u.pn * BM * g.ldb); }
; #define PG8_STAGE(bufoff, gbase, voff) do { if constexpr (VAR != 1 && VAR != 3) { _Pragma("unroll") for (int _i = 0; _i < 2; ++_i) \
;         asm volatile("s_mov_b32 m0, %2\n\ts_nop 0\n\tglobal_load_lds_dwordx4 %0, %1" :: "v"((voff)[_i]), "s"((const char*)(gbase)), "s"(ldsbase + (unsigned)((bufoff) + _i * 8192)) : "memory", "m0"); } } while (0)
; #define PG8_WAIT_V(n) asm volatile("s_waitcnt vmcnt(" #n ")" ::: "memory")
; #define PG8_BAR do { if constexpr (VAR != 3) __builtin_amdgcn_s_barrier(); } while (0)
;     ...
;     const char* cA = unitA(g, cur); const char* cB = unitB(g, cur);
;     PG8_STAGE(PG8_SB(0, 0), cB, voffB); PG8_STAGE(PG8_SB(0, 1), cB + hstepB, voffB); PG8_STAGE(PG8_SA(0, 0), cA, voffA); PG8_STAGE(PG8_SA(0, 1), cA + hstepA, voffA);
;     if (wr == 1) PG8_BAR;
;     PG8_WAIT_V(2); PG8_BAR;
;     PG8_STAGE(PG8_SB(1, 0), cB + kstep, voffB); PG8_STAGE(PG8_SA(1, 0), cA + kstep, voffA); PG8_STAGE(PG8_SB(1, 1), cB + hstepB + kstep, voffB);
;     PG8_WAIT_V(6); PG8_BAR;
; __global__ void __launch_bounds__(NWAVES * 64, 2) fwd_kernel(Args args) {
;     ...
;         { pg8::Gemm g{MEMN, WKV, DM, DM, DM, 1, 1 << 30, 0, 0, 0, 0, 0}; pg8::BatchOrder S; S.init(MMEM / 256, 2 * DM / 256, 1, G, vcu);
;           pg8::EpiBf16 E{KV, 2 * DM, nullptr, 1.0f, 1, 0, 0};
;           pg8::gemm_phase(ring, scr, g, S, E); }
.LBB0_336:
	v_readlane_b32 s36, v244, 2
	v_readlane_b32 s50, v244, 16
	v_readlane_b32 s51, v244, 17
	s_add_u32 s12, s50, 0x5100000
	s_addc_u32 s13, s51, 0
	s_add_u32 s58, s50, 0xd100000
	s_addc_u32 s59, s51, 0
	s_add_u32 s0, s50, 0x15100000
	s_addc_u32 s1, s51, 0
	s_add_u32 s8, s50, 0x26500000
	v_readlane_b32 s37, v244, 3
	v_readlane_b32 s38, v244, 4
	v_readlane_b32 s39, v244, 5
	v_readlane_b32 s40, v244, 6
	v_readlane_b32 s41, v244, 7
	v_readlane_b32 s42, v244, 8
	v_readlane_b32 s43, v244, 9
	v_readlane_b32 s44, v244, 10
	v_readlane_b32 s45, v244, 11
	v_readlane_b32 s46, v244, 12
	v_readlane_b32 s47, v244, 13
	v_readlane_b32 s48, v244, 14
	v_readlane_b32 s49, v244, 15
	v_writelane_b32 v244, s0, 45
	s_addc_u32 s9, s51, 0
	s_nop 0
	v_writelane_b32 v244, s1, 46
	s_add_u32 s0, s48, 0x4000000
	s_addc_u32 s1, s49, 0
	v_writelane_b32 v244, s0, 47
	s_nop 1
	v_writelane_b32 v244, s1, 48
	s_add_u32 s0, s48, 0x8400000
	s_addc_u32 s1, s49, 0
	v_writelane_b32 v244, s0, 49
	s_cmp_lt_i32 s96, 2
	s_nop 0
	v_writelane_b32 v244, s1, 50
	s_cselect_b64 s[0:1], -1, 0
	s_cmp_gt_i32 s97, 1
	s_cselect_b64 s[2:3], -1, 0
	s_and_b64 s[0:1], s[0:1], s[2:3]
	s_andn2_b64 vcc, exec, s[0:1]
	s_cbranch_vccnz .LBB0_626
	v_lshlrev_b32_e32 v130, 4, v0
	v_and_b32_e32 v1, 32, v0
	v_bitop3_b32 v1, v130, v1, 48 bitop3:0x6c
	s_waitcnt vmcnt(47)
	v_lshrrev_b32_e32 v4, 1, v0
	v_and_or_b32 v138, v0, 64, v1
	v_lshrrev_b32_e32 v1, 5, v0
	v_and_b32_e32 v144, 24, v4
	v_bfe_u32 v4, v0, 3, 25
	v_bfe_u32 v2, v0, 2, 4
	v_and_b32_e32 v1, 4, v1
	v_bfe_u32 v3, v0, 2, 2
	v_or_b32_e32 v4, 64, v4
	s_movk_i32 s0, 0x70
	v_or3_b32 v3, v1, v3, v144
	v_lshrrev_b32_e32 v1, 3, v0
	v_and_or_b32 v141, v4, s0, v2
	s_movk_i32 s0, 0x60
	v_readfirstlane_b32 s3, v0
	v_and_or_b32 v140, v1, 48, v2
	v_and_or_b32 v139, v1, 32, v3
	v_and_or_b32 v142, v4, s0, v3
	v_lshlrev_b32_e32 v2, 6, v0
	v_lshlrev_b32_e32 v3, 2, v0
	s_lshr_b32 s5, s3, 6
	v_lshlrev_b32_e32 v149, 1, v144
	v_and_b32_e32 v2, 0x3c0, v2
	v_and_b32_e32 v3, 32, v3
	v_and_b32_e32 v145, 15, v0
	v_lshl_or_b32 v1, v140, 13, v138
	v_lshl_or_b32 v146, v139, 13, v138
	v_lshl_or_b32 v147, v141, 13, v138
	v_lshl_or_b32 v148, v142, 13, v138
	s_cmpk_gt_i32 s34, 0x7f
	v_bitop3_b32 v150, v149, v3, v2 bitop3:0x36
	s_cbranch_scc1 .LBB0_353
	s_lshl_b32 s0, s5, 10
	v_readlane_b32 s36, v244, 2
	s_lshr_b32 s6, s3, 8
	s_add_i32 s19, s0, 0
	v_readlane_b32 s50, v244, 16
	v_readlane_b32 s51, v244, 17
	s_add_u32 s21, s50, 0x25d00000
	s_addc_u32 s23, s51, 0
	s_ashr_i32 s24, s34, 31
	s_lshr_b32 s0, s24, 25
	s_add_i32 s0, s34, s0
	s_and_b32 s0, s0, 0xff80
	s_sub_i32 s0, s34, s0
	s_bfe_i32 s1, s0, 0x80000
	s_bfe_u32 s1, s1, 0x5000a
	s_add_i32 s1, s0, s1
	s_bfe_i32 s2, s1, 0x80000
	s_and_b32 s1, s1, 0xffe0
	s_sext_i32_i16 s2, s2
	s_sub_i32 s4, s0, s1
	s_lshr_b32 s2, s2, 5
	s_bfe_i64 s[14:15], s[4:5], 0x80000
	s_bfe_i64 s[0:1], s[2:3], 0x100000
	s_lshl_b64 s[14:15], s[14:15], 21
	s_add_u32 s90, s86, s14
	s_addc_u32 s91, s87, s15
	s_add_i32 s25, s19, 0x10000
	s_mov_b32 m0, s25
	s_nop 0
	global_load_lds_dwordx4 v146, s[90:91]
	s_add_i32 s26, s19, 0x12000
	s_mov_b32 m0, s26
	s_nop 0
	global_load_lds_dwordx4 v148, s[90:91]
	s_add_u32 s14, s90, 0x100000
	s_addc_u32 s15, s91, 0
	s_add_i32 s27, s19, 0x14000
	s_mov_b32 m0, s27
	s_nop 0
	global_load_lds_dwordx4 v146, s[14:15]
	s_add_i32 s28, s19, 0x16000
	s_lshl_b64 s[0:1], s[0:1], 21
	s_mov_b32 m0, s28
	s_nop 0
	global_load_lds_dwordx4 v148, s[14:15]
	s_add_u32 s92, s21, s0
	s_addc_u32 s93, s23, s1
	s_mov_b32 m0, s19
	s_nop 0
	global_load_lds_dwordx4 v1, s[92:93]
	s_add_i32 s29, s19, 0x2000
	s_mov_b32 m0, s29
	s_nop 0
	global_load_lds_dwordx4 v147, s[92:93]
	s_add_u32 s14, s92, 0x100000
	s_addc_u32 s15, s93, 0
	s_add_i32 s30, s19, 0x4000
	s_mov_b32 m0, s30
	s_nop 0
	global_load_lds_dwordx4 v1, s[14:15]
	s_add_i32 s31, s19, 0x6000
	s_mov_b32 m0, s31
	s_nop 0
	global_load_lds_dwordx4 v147, s[14:15]
	s_cmp_eq_u32 s6, 1
	s_mov_b32 s17, 0
	s_cselect_b64 s[0:1], -1, 0
	s_cmp_lg_u32 s6, 1
	v_readlane_b32 s37, v244, 3
	v_readlane_b32 s38, v244, 4
	v_readlane_b32 s39, v244, 5
	v_readlane_b32 s40, v244, 6
	v_readlane_b32 s41, v244, 7
	v_readlane_b32 s42, v244, 8
	v_readlane_b32 s43, v244, 9
	v_readlane_b32 s44, v244, 10
	v_readlane_b32 s45, v244, 11
	v_readlane_b32 s46, v244, 12
	v_readlane_b32 s47, v244, 13
	v_readlane_b32 s48, v244, 14
	v_readlane_b32 s49, v244, 15
	s_cbranch_scc1 .LBB0_340
	s_barrier

; #define LAS __attribute__((address_space(3)))
; __device__ __forceinline__ unsigned cvt_pk_bf16(float lo, float hi) { unsigned r; asm volatile("v_cvt_pk_bf16_f32 %0, %1, %2" : "=v"(r) : "v"(lo), "v"(hi)); return r; }
;     __device__ __forceinline__ void operator()(EPI_ARGS) const {
;         const int row0 = u.pm * BM + wr * 64 + fr, c8 = wc * 32 + 8 * fq, pn = u.pn + pn_off;
;         if (I8) { if (__builtin_amdgcn_readfirstlane(((LAS int*)rtab)[256]) != u.pm) { EPI_BAR(); if (threadIdx.x < 256) rtab[threadIdx.x] = sA[u.pm * BM + threadIdx.x]; if (threadIdx.x == 0) ((LAS int*)rtab)[256] = u.pm; EPI_BAR(); } }
;         if (I8 || pn < 32) {
;             const bool glu = I8 || pn < 16;
;             bf16* base = (glu ? U0 : CH) + (size_t)((pn & 15) * HALF + c8);
;             f32x4 sb[2][2];
;             if (I8) {
; #pragma unroll
;                 for (int bj = 0; bj < 2; ++bj)
; #pragma unroll
;                     for (int n = 0; n < 2; ++n) { const u32x4 cm = *(const u32x4*)(cmaxB + pn * BM + bj * HALF + c8 + 4 * n); sb[bj][n] = (f32x4){__uint_as_float(cm.x), __uint_as_float(cm.y), __uint_as_float(cm.z), __uint_as_float(cm.w)} * (1.0f / 127.0f); } }
; #pragma unroll
;             for (int ai = 0; ai < 2; ++ai)
; #pragma unroll
;                 for (int m = 0; m < 4; ++m) {
;                     const float rs = I8 ? rtab[wr * 64 + fr + ai * HALF + m * 16] : 1.0f;
;                     f32x4 o[2];
; #pragma unroll
;                     for (int n = 0; n < 2; ++n) { f32x4 a = acc[ai][0][m][n], b = acc[ai][1][m][n];
;                         if (I8) { const i32x4 ia = __builtin_bit_cast(i32x4, a), ib = __builtin_bit_cast(i32x4, b);
;                             a = (f32x4){(float)ia[0], (float)ia[1], (float)ia[2], (float)ia[3]} * (sb[0][n] * rs); b = (f32x4){(float)ib[0], (float)ib[1], (float)ib[2], (float)ib[3]} * (sb[1][n] * rs); }
; #pragma unroll
;                         for (int e = 0; e < 4; ++e) o[n][e] = glu ? a[e] * fast_sigmoid(b[e]) : a[e] * b[e]; }
;                     u32x4 w; w.x = cvt_pk_bf16(o[0][0], o[0][1]); w.y = cvt_pk_bf16(o[0][2], o[0][3]); w.z = cvt_pk_bf16(o[1][0], o[1][1]); w.w = cvt_pk_bf16(o[1][2], o[1][3]);
;                     *(u32x4*)(base + (size_t)(row0 + ai * HALF + m * 16) * CWID) = w; }
.LBB0_564:
	s_nop 7
	v_lshl_add_u32 v245, s0, 8, v151
	v_mul_u32_u24_e32 v245, 0x1080, v245
	v_bfe_u32 v246, v0, 6, 2
	v_bfe_u32 v255, v0, 4, 2
	v_lshlrev_b32_e32 v246, 6, v246
	v_lshl_add_u32 v246, v255, 4, v246
	v_add_u32_e32 v245, v245, v246
	s_cmp_gt_i32 s91, 15
	s_cbranch_scc1 .Lmy_p1b_bg
	s_lshl_b32 s0, s91, 8
	v_add_u32_e32 v245, s0, v245
	v_readlane_b32 s0, v244, 47
	v_readlane_b32 s1, v244, 48
	s_nop 4
	v_pk_mul_f32 v[126:127], v[126:127], v[122:123]
	v_pk_mul_f32 v[128:129], v[128:129], v[124:125]
	v_cvt_pk_bf16_f32 v136, v126, v127
	v_cvt_pk_bf16_f32 v137, v128, v129
	v_pk_mul_f32 v[118:119], v[118:119], v[114:115]
	v_pk_mul_f32 v[120:121], v[120:121], v[116:117]
	v_cvt_pk_bf16_f32 v138, v118, v119
	v_cvt_pk_bf16_f32 v139, v120, v121
	global_store_dwordx4 v245, v[136:139], s[0:1]
	v_pk_mul_f32 v[110:111], v[110:111], v[106:107]
	v_pk_mul_f32 v[112:113], v[112:113], v[108:109]
	v_cvt_pk_bf16_f32 v140, v110, v111
	v_cvt_pk_bf16_f32 v141, v112, v113
	v_pk_mul_f32 v[102:103], v[102:103], v[98:99]
	v_pk_mul_f32 v[104:105], v[104:105], v[100:101]
	v_cvt_pk_bf16_f32 v142, v102, v103
	v_cvt_pk_bf16_f32 v143, v104, v105
	v_add_u32_e32 v246, 0x10800, v245
	global_store_dwordx4 v246, v[140:143], s[0:1]
	v_pk_mul_f32 v[94:95], v[94:95], v[90:91]
	v_pk_mul_f32 v[96:97], v[96:97], v[92:93]
	v_cvt_pk_bf16_f32 v158, v94, v95
	v_cvt_pk_bf16_f32 v159, v96, v97
	v_pk_mul_f32 v[86:87], v[86:87], v[82:83]
	v_pk_mul_f32 v[88:89], v[88:89], v[84:85]
	v_cvt_pk_bf16_f32 v160, v86, v87
	v_cvt_pk_bf16_f32 v161, v88, v89
	v_add_u32_e32 v255, 0x21000, v245
	global_store_dwordx4 v255, v[158:161], s[0:1]
	v_pk_mul_f32 v[78:79], v[78:79], v[74:75]
	v_pk_mul_f32 v[80:81], v[80:81], v[76:77]
	v_cvt_pk_bf16_f32 v162, v78, v79
	v_cvt_pk_bf16_f32 v163, v80, v81
	v_pk_mul_f32 v[70:71], v[70:71], v[66:67]
	v_pk_mul_f32 v[72:73], v[72:73], v[68:69]
	v_cvt_pk_bf16_f32 v164, v70, v71
	v_cvt_pk_bf16_f32 v165, v72, v73
	v_add_u32_e32 v246, 0x31800, v245
	global_store_dwordx4 v246, v[162:165], s[0:1]
	v_pk_mul_f32 v[62:63], v[62:63], v[58:59]
	v_pk_mul_f32 v[64:65], v[64:65], v[60:61]
	v_cvt_pk_bf16_f32 v166, v62, v63
	v_cvt_pk_bf16_f32 v167, v64, v65
	v_pk_mul_f32 v[54:55], v[54:55], v[50:51]
	v_pk_mul_f32 v[56:57], v[56:57], v[52:53]
	v_cvt_pk_bf16_f32 v168, v54, v55
	v_cvt_pk_bf16_f32 v169, v56, v57
	v_add_u32_e32 v255, 0x84000, v245
	global_store_dwordx4 v255, v[166:169], s[0:1]
	v_pk_mul_f32 v[46:47], v[46:47], v[42:43]
	v_pk_mul_f32 v[48:49], v[48:49], v[44:45]
	v_cvt_pk_bf16_f32 v170, v46, v47
	v_cvt_pk_bf16_f32 v171, v48, v49
	v_pk_mul_f32 v[38:39], v[38:39], v[34:35]
	v_pk_mul_f32 v[40:41], v[40:41], v[36:37]
	v_cvt_pk_bf16_f32 v172, v38, v39
	v_cvt_pk_bf16_f32 v173, v40, v41
	v_add_u32_e32 v246, 0x94800, v245
	global_store_dwordx4 v246, v[170:173], s[0:1]
	v_pk_mul_f32 v[30:31], v[30:31], v[26:27]
	v_pk_mul_f32 v[32:33], v[32:33], v[28:29]
	v_cvt_pk_bf16_f32 v174, v30, v31
	v_cvt_pk_bf16_f32 v175, v32, v33
	v_pk_mul_f32 v[22:23], v[22:23], v[18:19]
	v_pk_mul_f32 v[24:25], v[24:25], v[20:21]
	v_cvt_pk_bf16_f32 v176, v22, v23
	v_cvt_pk_bf16_f32 v177, v24, v25
	v_add_u32_e32 v255, 0xa5000, v245
	global_store_dwordx4 v255, v[174:177], s[0:1]
	v_pk_mul_f32 v[14:15], v[14:15], v[10:11]
	v_pk_mul_f32 v[16:17], v[16:17], v[12:13]
	v_cvt_pk_bf16_f32 v178, v14, v15
	v_cvt_pk_bf16_f32 v179, v16, v17
	v_pk_mul_f32 v[6:7], v[6:7], v[2:3]
	v_pk_mul_f32 v[8:9], v[8:9], v[4:5]
	v_cvt_pk_bf16_f32 v180, v6, v7
	v_cvt_pk_bf16_f32 v181, v8, v9
	v_add_u32_e32 v246, 0xb5800, v245
	global_store_dwordx4 v246, v[178:181], s[0:1]
	s_branch .Lmy_p1b_done
; __device__ __forceinline__ unsigned cvt_pk_bf16(float lo, float hi) { unsigned r; asm volatile("v_cvt_pk_bf16_f32 %0, %1, %2" : "=v"(r) : "v"(lo), "v"(hi)); return r; }
;     __device__ __forceinline__ void operator()(EPI_ARGS) const {
;     ...
;         } else {
;             bf16* base = BG + (size_t)((pn - 32) * BM + c8);
; #pragma unroll
;             for (int ai = 0; ai < 2; ++ai)
; #pragma unroll
;                 for (int m = 0; m < 4; ++m)
; #pragma unroll
;                     for (int bj = 0; bj < 2; ++bj) { const f32x4 v0 = acc[ai][bj][m][0], v1 = acc[ai][bj][m][1];
;                         u32x4 w; w.x = cvt_pk_bf16(v0[0], v0[1]); w.y = cvt_pk_bf16(v0[2], v0[3]); w.z = cvt_pk_bf16(v1[0], v1[1]); w.w = cvt_pk_bf16(v1[2], v1[3]);
;                         *(u32x4*)(base + (size_t)(row0 + ai * HALF + m * 16) * CWID + bj * HALF) = w; }
;         }
.Lmy_p1b_bg:
	s_sub_i32 s0, s91, 16
	s_lshl_b32 s0, s0, 9
	v_add_u32_e32 v245, s0, v245
	v_readlane_b32 s0, v244, 49
	v_readlane_b32 s1, v244, 50
	s_nop 4
	v_cvt_pk_bf16_f32 v136, v126, v127
	v_cvt_pk_bf16_f32 v137, v128, v129
	v_cvt_pk_bf16_f32 v138, v118, v119
	v_cvt_pk_bf16_f32 v139, v120, v121
	global_store_dwordx4 v245, v[136:139], s[0:1]
	v_cvt_pk_bf16_f32 v140, v122, v123
	v_cvt_pk_bf16_f32 v141, v124, v125
	v_cvt_pk_bf16_f32 v142, v114, v115
	v_cvt_pk_bf16_f32 v143, v116, v117
	global_store_dwordx4 v245, v[140:143], s[0:1] offset:256
	v_add_u32_e32 v246, 0x10800, v245
	v_cvt_pk_bf16_f32 v158, v110, v111
	v_cvt_pk_bf16_f32 v159, v112, v113
	v_cvt_pk_bf16_f32 v160, v102, v103
	v_cvt_pk_bf16_f32 v161, v104, v105
	global_store_dwordx4 v246, v[158:161], s[0:1]
	v_cvt_pk_bf16_f32 v162, v106, v107
	v_cvt_pk_bf16_f32 v163, v108, v109
	v_cvt_pk_bf16_f32 v164, v98, v99
	v_cvt_pk_bf16_f32 v165, v100, v101
	global_store_dwordx4 v246, v[162:165], s[0:1] offset:256
	v_add_u32_e32 v255, 0x21000, v245
	v_cvt_pk_bf16_f32 v166, v94, v95
	v_cvt_pk_bf16_f32 v167, v96, v97
	v_cvt_pk_bf16_f32 v168, v86, v87
	v_cvt_pk_bf16_f32 v169, v88, v89
	global_store_dwordx4 v255, v[166:169], s[0:1]
	v_cvt_pk_bf16_f32 v170, v90, v91
	v_cvt_pk_bf16_f32 v171, v92, v93
	v_cvt_pk_bf16_f32 v172, v82, v83
	v_cvt_pk_bf16_f32 v173, v84, v85
	global_store_dwordx4 v255, v[170:173], s[0:1] offset:256
	v_add_u32_e32 v246, 0x31800, v245
	v_cvt_pk_bf16_f32 v174, v78, v79
	v_cvt_pk_bf16_f32 v175, v80, v81
	v_cvt_pk_bf16_f32 v176, v70, v71
	v_cvt_pk_bf16_f32 v177, v72, v73
	global_store_dwordx4 v246, v[174:177], s[0:1]
	v_cvt_pk_bf16_f32 v178, v74, v75
	v_cvt_pk_bf16_f32 v179, v76, v77
	v_cvt_pk_bf16_f32 v180, v66, v67
	v_cvt_pk_bf16_f32 v181, v68, v69
	global_store_dwordx4 v246, v[178:181], s[0:1] offset:256
	v_add_u32_e32 v255, 0x84000, v245
	v_cvt_pk_bf16_f32 v182, v62, v63
	v_cvt_pk_bf16_f32 v183, v64, v65
	v_cvt_pk_bf16_f32 v184, v54, v55
	v_cvt_pk_bf16_f32 v185, v56, v57
	global_store_dwordx4 v255, v[182:185], s[0:1]
	v_cvt_pk_bf16_f32 v186, v58, v59
	v_cvt_pk_bf16_f32 v187, v60, v61
	v_cvt_pk_bf16_f32 v188, v50, v51
	v_cvt_pk_bf16_f32 v189, v52, v53
	global_store_dwordx4 v255, v[186:189], s[0:1] offset:256
	v_add_u32_e32 v246, 0x94800, v245
	v_cvt_pk_bf16_f32 v190, v46, v47
	v_cvt_pk_bf16_f32 v191, v48, v49
	v_cvt_pk_bf16_f32 v192, v38, v39
	v_cvt_pk_bf16_f32 v193, v40, v41
	global_store_dwordx4 v246, v[190:193], s[0:1]
	v_cvt_pk_bf16_f32 v194, v42, v43
	v_cvt_pk_bf16_f32 v195, v44, v45
	v_cvt_pk_bf16_f32 v196, v34, v35
	v_cvt_pk_bf16_f32 v197, v36, v37
	global_store_dwordx4 v246, v[194:197], s[0:1] offset:256
	v_add_u32_e32 v255, 0xa5000, v245
	v_cvt_pk_bf16_f32 v198, v30, v31
	v_cvt_pk_bf16_f32 v199, v32, v33
	v_cvt_pk_bf16_f32 v200, v22, v23
	v_cvt_pk_bf16_f32 v201, v24, v25
	global_store_dwordx4 v255, v[198:201], s[0:1]
	v_cvt_pk_bf16_f32 v202, v26, v27
	v_cvt_pk_bf16_f32 v203, v28, v29
	v_cvt_pk_bf16_f32 v204, v18, v19
	v_cvt_pk_bf16_f32 v205, v20, v21
	global_store_dwordx4 v255, v[202:205], s[0:1] offset:256
	v_add_u32_e32 v246, 0xb5800, v245
	v_cvt_pk_bf16_f32 v206, v14, v15
	v_cvt_pk_bf16_f32 v207, v16, v17
	v_cvt_pk_bf16_f32 v208, v6, v7
	v_cvt_pk_bf16_f32 v209, v8, v9
	global_store_dwordx4 v246, v[206:209], s[0:1]
	v_cvt_pk_bf16_f32 v210, v10, v11
	v_cvt_pk_bf16_f32 v211, v12, v13
	v_cvt_pk_bf16_f32 v212, v2, v3
	v_cvt_pk_bf16_f32 v213, v4, v5
	global_store_dwordx4 v246, v[210:213], s[0:1] offset:256
.Lmy_p1b_done:
	s_andn2_b64 vcc, exec, s[2:3]
	s_mov_b64 s[0:1], -1
	s_cbranch_vccnz .LBB0_557
.LBB0_569:
	s_andn2_b64 vcc, exec, s[4:5]
	s_cbranch_vccnz .LBB0_556
	s_barrier
	s_branch .LBB0_556

; #define GAS __attribute__((address_space(1)))
; __device__ __forceinline__ unsigned cvt_pk_bf16(float lo, float hi) { unsigned r; asm volatile("v_cvt_pk_bf16_f32 %0, %1, %2" : "=v"(r) : "v"(lo), "v"(hi)); return r; }
; __device__ __forceinline__ float bf_lo(unsigned w) { return __uint_as_float(w << 16); }
; __device__ __forceinline__ float bf_hi(unsigned w) { return __uint_as_float(w & 0xffff0000u); }
; __global__ void __launch_bounds__(NWAVES * 64, 2) fwd_kernel(Args args) {
;     ...
;         for (size_t i = (size_t)vcu * 512 + tid; i < (size_t)(MTOK / 4) * (CWID / 8); i += (size_t)G * 512) {
;             const int rq = (int)(i >> 8), ch = (int)(i & 255), row0 = rq * 4; const bool first = (row0 % SEQ) == 0;
;             const u32x4 z4 = (u32x4){0u, 0u, 0u, 0u};
;             u32x4 cv[6], bg[4];
; #pragma unroll
;             for (int r = 0; r < 6; ++r) cv[r] = (first && r < 2) ? z4 : *(const GAS u32x4*)(CH + (size_t)(row0 - 2 + r) * CWID + ch * 8);
; #pragma unroll
;             for (int r = 0; r < 4; ++r) bg[r] = *(const GAS u32x4*)(BG + (size_t)(row0 + r) * CWID + ch * 8);
;             float w0[8], w1[8], w2[8];
; #pragma unroll
;             for (int h = 0; h < 2; ++h) { const f32x4 a = *(const GAS f32x4*)(conv_b_w + ch * 8 + 4 * h), b = *(const GAS f32x4*)(conv_b_w + CWID + ch * 8 + 4 * h), c = *(const GAS f32x4*)(conv_b_w + 2 * CWID + ch * 8 + 4 * h);
; #pragma unroll
;                 for (int e = 0; e < 4; ++e) { w0[4 * h + e] = a[e]; w1[4 * h + e] = b[e]; w2[4 * h + e] = c[e]; } }
; #pragma unroll
;             for (int r = 0; r < 4; ++r) { unsigned ow[4];
; #pragma unroll
;                 for (int p_ = 0; p_ < 4; ++p_) {
;                     const float lo_ = bf_lo(bg[r][p_]) * (w0[2 * p_] * bf_lo(cv[r][p_]) + w1[2 * p_] * bf_lo(cv[r + 1][p_]) + w2[2 * p_] * bf_lo(cv[r + 2][p_]));
;                     const float hi_ = bf_hi(bg[r][p_]) * (w0[2 * p_ + 1] * bf_hi(cv[r][p_]) + w1[2 * p_ + 1] * bf_hi(cv[r + 1][p_]) + w2[2 * p_ + 1] * bf_hi(cv[r + 2][p_]));
;                     ow[p_] = cvt_pk_bf16(lo_, hi_); }
;                 *(GAS u32x4*)(MIX + (size_t)(row0 + r) * DM + CWID + ch * 8) = (u32x4){ow[0], ow[1], ow[2], ow[3]}; }
;         }
.LBB0_655:
	s_or_b64 exec, exec, s[14:15]
	v_lshl_add_u64 v[10:11], v[48:49], 0, v[44:45]
	global_load_dwordx4 v[18:21], v[54:55], off
	global_load_dwordx4 v[14:17], v[50:51], off
	global_load_dwordx4 v[6:9], v[54:55], off offset:16
	global_load_dwordx4 v[2:5], v[50:51], off offset:16
	v_lshl_add_u64 v[32:33], v[46:47], 0, v[44:45]
	global_load_dwordx4 v[84:87], v[10:11], off
	global_load_dwordx4 v[88:91], v[32:33], off
	v_or_b32_e32 v122, 1, v82
	v_add_co_u32_e32 v10, vcc, 0x1080, v32
	v_mul_u32_u24_e32 v44, 0x1080, v122
	v_lshl_add_u64 v[12:13], v[48:49], 0, v[44:45]
	v_addc_co_u32_e32 v11, vcc, 0, v33, vcc
	global_load_dwordx4 v[92:95], v[12:13], off
	global_load_dwordx4 v[96:99], v[10:11], off
	global_load_dwordx4 v[22:25], v[52:53], off
	s_nop 0
	global_load_dwordx4 v[10:13], v[52:53], off offset:16
	v_or_b32_e32 v123, 3, v30
	v_mov_b32_e32 v31, v45
	v_or_b32_e32 v124, 2, v82
	s_waitcnt vmcnt(10)
	v_lshlrev_b32_e32 v77, 16, v26
	v_and_b32_e32 v75, 0xffff0000, v26
	v_mul_u32_u24_e32 v30, 0x1080, v123
	v_add_co_u32_e32 v26, vcc, 0x2100, v32
	v_lshlrev_b32_e32 v73, 16, v27
	v_and_b32_e32 v69, 0xffff0000, v27
	v_lshl_add_u64 v[34:35], v[46:47], 0, v[30:31]
	v_mul_u32_u24_e32 v44, 0x1080, v124
	v_lshl_add_u64 v[36:37], v[48:49], 0, v[30:31]
	v_addc_co_u32_e32 v27, vcc, 0, v33, vcc
	v_lshlrev_b32_e32 v65, 16, v28
	v_and_b32_e32 v63, 0xffff0000, v28
	v_lshlrev_b32_e32 v61, 16, v29
	v_and_b32_e32 v59, 0xffff0000, v29
	v_lshl_add_u64 v[66:67], v[48:49], 0, v[44:45]
	global_load_dwordx4 v[26:29], v[26:27], off
	s_nop 0
	global_load_dwordx4 v[30:33], v[34:35], off
	global_load_dwordx4 v[100:103], v[66:67], off
	s_nop 0
	global_load_dwordx4 v[34:37], v[36:37], off
	v_lshlrev_b32_e32 v121, 16, v38
	v_lshlrev_b32_e32 v44, 13, v82
	v_lshl_add_u64 v[82:83], s[60:61], 0, v[44:45]
	v_lshl_add_u64 v[82:83], v[82:83], 0, v[56:57]
	v_add_co_u32_e32 v82, vcc, s6, v82
	v_lshl_add_u64 v[42:43], v[42:43], 0, s[4:5]
	s_nop 0
	v_addc_co_u32_e32 v83, vcc, 0, v83, vcc
	s_waitcnt vmcnt(13)
	v_mov_b32_e32 v104, v18
	s_waitcnt vmcnt(12)
	v_mov_b32_e32 v105, v14
	s_waitcnt vmcnt(11)
	v_mov_b32_e32 v70, v8
	s_waitcnt vmcnt(10)
	v_mov_b32_e32 v71, v4
	s_waitcnt vmcnt(9)
	v_lshlrev_b32_e32 v125, 16, v84
	s_waitcnt vmcnt(8)
	v_lshlrev_b32_e32 v76, 16, v88
	v_and_b32_e32 v126, 0xffff0000, v84
	v_lshlrev_b32_e32 v127, 16, v85
	v_and_b32_e32 v128, 0xffff0000, v85
	v_lshlrev_b32_e32 v60, 16, v91
	v_pk_mul_f32 v[84:85], v[104:105], v[76:77]
	v_pk_mul_f32 v[116:117], v[70:71], v[60:61]
	s_waitcnt vmcnt(6)
	v_lshlrev_b32_e32 v120, 16, v96
	s_waitcnt vmcnt(5)
	v_fma_f32 v61, v22, v121, v85
	v_mov_b32_e32 v106, v19
	v_mov_b32_e32 v107, v15
	v_mov_b32_e32 v80, v6
	v_mov_b32_e32 v81, v2
	v_and_b32_e32 v74, 0xffff0000, v88
	v_lshlrev_b32_e32 v64, 16, v90
	v_add_f32_e32 v61, v84, v61
	v_pk_mul_f32 v[84:85], v[104:105], v[120:121]
	v_lshlrev_b32_e32 v129, 16, v86
	v_and_b32_e32 v130, 0xffff0000, v86
	v_lshlrev_b32_e32 v131, 16, v87
	v_and_b32_e32 v132, 0xffff0000, v87
	v_pk_mul_f32 v[86:87], v[106:107], v[74:75]
	v_pk_mul_f32 v[112:113], v[80:81], v[64:65]
	v_fma_f32 v65, v22, v76, v85
	v_and_b32_e32 v85, 0xffff0000, v38
	v_fma_f32 v38, v23, v85, v87
	v_add_f32_e32 v65, v84, v65
	v_and_b32_e32 v84, 0xffff0000, v96
	v_add_f32_e32 v38, v86, v38
	v_mov_b32_e32 v108, v20
	v_mov_b32_e32 v109, v16
	v_lshlrev_b32_e32 v72, 16, v89
	v_mul_f32_e32 v61, v61, v125
	v_mul_f32_e32 v38, v38, v126
	v_pk_mul_f32 v[86:87], v[106:107], v[84:85]
	v_and_b32_e32 v68, 0xffff0000, v89
	v_pk_mul_f32 v[88:89], v[108:109], v[72:73]
	v_cvt_pk_bf16_f32 v38, v61, v38
	v_fma_f32 v61, v23, v74, v87
	v_lshlrev_b32_e32 v87, 16, v39
	v_add_f32_e32 v61, v86, v61
	v_lshlrev_b32_e32 v86, 16, v97
	v_fma_f32 v73, v24, v87, v89
	v_mov_b32_e32 v110, v21
	v_mov_b32_e32 v111, v17
	v_add_f32_e32 v73, v88, v73
	v_pk_mul_f32 v[88:89], v[108:109], v[86:87]
	v_and_b32_e32 v62, 0xffff0000, v90
	v_and_b32_e32 v58, 0xffff0000, v91
	v_pk_mul_f32 v[90:91], v[110:111], v[68:69]
	v_fma_f32 v77, v24, v72, v89
	v_and_b32_e32 v89, 0xffff0000, v39
	v_fma_f32 v39, v25, v89, v91
	v_add_f32_e32 v77, v88, v77
	v_and_b32_e32 v88, 0xffff0000, v97
	v_add_f32_e32 v39, v90, v39
	v_lshlrev_b32_e32 v44, 16, v92
	v_mul_f32_e32 v73, v73, v127
	v_mul_f32_e32 v39, v39, v128
	v_pk_mul_f32 v[90:91], v[110:111], v[88:89]
	v_mul_f32_e32 v44, v65, v44
	v_and_b32_e32 v65, 0xffff0000, v92
	v_cvt_pk_bf16_f32 v39, v73, v39
	v_fma_f32 v73, v25, v68, v91
	v_mul_f32_e32 v61, v61, v65
	v_lshlrev_b32_e32 v65, 16, v93
	v_add_f32_e32 v73, v90, v73
	v_lshlrev_b32_e32 v91, 16, v40
	v_lshlrev_b32_e32 v90, 16, v98
	v_mov_b32_e32 v78, v7
	v_mov_b32_e32 v79, v3
	v_mul_f32_e32 v65, v77, v65
	v_and_b32_e32 v77, 0xffff0000, v93
	v_pk_mul_f32 v[92:93], v[80:81], v[90:91]
	v_pk_mul_f32 v[114:115], v[78:79], v[62:63]
	s_waitcnt vmcnt(4)
	v_fma_f32 v87, v10, v64, v93
	v_and_b32_e32 v93, 0xffff0000, v40
	v_fma_f32 v85, v10, v91, v113
	v_fma_f32 v40, v11, v93, v115
	v_add_f32_e32 v85, v112, v85
	v_add_f32_e32 v87, v92, v87
	v_and_b32_e32 v92, 0xffff0000, v98
	v_add_f32_e32 v40, v114, v40
	v_mul_f32_e32 v85, v85, v129
	v_mul_f32_e32 v40, v40, v130
	v_pk_mul_f32 v[96:97], v[78:79], v[92:93]
	v_cvt_pk_bf16_f32 v40, v85, v40
	v_mul_f32_e32 v73, v73, v77
	v_fma_f32 v85, v11, v62, v97
	v_add_f32_e32 v85, v96, v85
	v_lshlrev_b32_e32 v96, 16, v99
	v_lshlrev_b32_e32 v97, 16, v41
	v_lshlrev_b32_e32 v77, 16, v94
	v_pk_mul_f32 v[112:113], v[70:71], v[96:97]
	v_mul_f32_e32 v77, v87, v77
	v_and_b32_e32 v87, 0xffff0000, v94
	v_fma_f32 v91, v12, v60, v113
	v_mov_b32_e32 v66, v9
	v_mov_b32_e32 v67, v5
	v_mul_f32_e32 v85, v85, v87
	v_lshlrev_b32_e32 v87, 16, v95
	v_add_f32_e32 v91, v112, v91
	v_pk_mul_f32 v[118:119], v[66:67], v[58:59]
	v_mul_f32_e32 v87, v91, v87
	v_and_b32_e32 v91, 0xffff0000, v95
	v_and_b32_e32 v95, 0xffff0000, v41
	v_fma_f32 v41, v13, v95, v119
	v_fma_f32 v89, v12, v97, v117
	v_add_f32_e32 v41, v118, v41
	v_add_f32_e32 v89, v116, v89
	v_and_b32_e32 v94, 0xffff0000, v99
	v_mul_f32_e32 v41, v41, v132
	v_mul_f32_e32 v89, v89, v131
	v_cvt_pk_bf16_f32 v41, v89, v41
	global_store_dwordx4 v[82:83], v[38:41], off
	v_pk_mul_f32 v[82:83], v[66:67], v[94:95]
	s_waitcnt vmcnt(2)
; #define GAS __attribute__((address_space(1)))
; __device__ __forceinline__ unsigned cvt_pk_bf16(float lo, float hi) { unsigned r; asm volatile("v_cvt_pk_bf16_f32 %0, %1, %2" : "=v"(r) : "v"(lo), "v"(hi)); return r; }
; __device__ __forceinline__ float bf_lo(unsigned w) { return __uint_as_float(w << 16); }
; __device__ __forceinline__ float bf_hi(unsigned w) { return __uint_as_float(w & 0xffff0000u); }
; __global__ void __launch_bounds__(NWAVES * 64, 2) fwd_kernel(Args args) {
;     ...
;         for (size_t i = (size_t)vcu * 512 + tid; i < (size_t)(MTOK / 4) * (CWID / 8); i += (size_t)G * 512) {
;             const int rq = (int)(i >> 8), ch = (int)(i & 255), row0 = rq * 4; const bool first = (row0 % SEQ) == 0;
;             const u32x4 z4 = (u32x4){0u, 0u, 0u, 0u};
;             u32x4 cv[6], bg[4];
; #pragma unroll
;             for (int r = 0; r < 6; ++r) cv[r] = (first && r < 2) ? z4 : *(const GAS u32x4*)(CH + (size_t)(row0 - 2 + r) * CWID + ch * 8);
; #pragma unroll
;             for (int r = 0; r < 4; ++r) bg[r] = *(const GAS u32x4*)(BG + (size_t)(row0 + r) * CWID + ch * 8);
;             float w0[8], w1[8], w2[8];
; #pragma unroll
;             for (int h = 0; h < 2; ++h) { const f32x4 a = *(const GAS f32x4*)(conv_b_w + ch * 8 + 4 * h), b = *(const GAS f32x4*)(conv_b_w + CWID + ch * 8 + 4 * h), c = *(const GAS f32x4*)(conv_b_w + 2 * CWID + ch * 8 + 4 * h);
; #pragma unroll
;                 for (int e = 0; e < 4; ++e) { w0[4 * h + e] = a[e]; w1[4 * h + e] = b[e]; w2[4 * h + e] = c[e]; } }
; #pragma unroll
;             for (int r = 0; r < 4; ++r) { unsigned ow[4];
; #pragma unroll
;                 for (int p_ = 0; p_ < 4; ++p_) {
;                     const float lo_ = bf_lo(bg[r][p_]) * (w0[2 * p_] * bf_lo(cv[r][p_]) + w1[2 * p_] * bf_lo(cv[r + 1][p_]) + w2[2 * p_] * bf_lo(cv[r + 2][p_]));
;                     const float hi_ = bf_hi(bg[r][p_]) * (w0[2 * p_ + 1] * bf_hi(cv[r][p_]) + w1[2 * p_ + 1] * bf_hi(cv[r + 1][p_]) + w2[2 * p_ + 1] * bf_hi(cv[r + 2][p_]));
;                     ow[p_] = cvt_pk_bf16(lo_, hi_); }
;                 *(GAS u32x4*)(MIX + (size_t)(row0 + r) * DM + CWID + ch * 8) = (u32x4){ow[0], ow[1], ow[2], ow[3]}; }
;         }
	v_and_b32_e32 v89, 0xffff0000, v103
	v_cvt_pk_bf16_f32 v38, v44, v61
	v_fma_f32 v41, v13, v58, v83
	v_lshlrev_b32_e32 v44, 13, v122
	v_add_f32_e32 v41, v82, v41
	v_lshl_add_u64 v[82:83], s[60:61], 0, v[44:45]
	v_lshl_add_u64 v[82:83], v[82:83], 0, v[56:57]
	v_mul_f32_e32 v41, v41, v91
	v_add_co_u32_e32 v82, vcc, s6, v82
	v_cvt_pk_bf16_f32 v39, v65, v73
	v_cvt_pk_bf16_f32 v40, v77, v85
	v_cvt_pk_bf16_f32 v41, v87, v41
	v_lshlrev_b32_e32 v61, 16, v100
	s_nop 0
	v_addc_co_u32_e32 v83, vcc, 0, v83, vcc
	global_store_dwordx4 v[82:83], v[38:41], off
	v_lshlrev_b32_e32 v44, 13, v124
	v_lshlrev_b32_e32 v73, 16, v101
	v_lshlrev_b32_e32 v41, 16, v26
	v_lshlrev_b32_e32 v40, 16, v30
	v_pk_mov_b32 v[76:77], v[40:41], v[76:77] op_sel:[1,0]
	v_lshl_add_u64 v[38:39], s[60:61], 0, v[44:45]
	v_pk_mul_f32 v[76:77], v[104:105], v[76:77]
	s_waitcnt vmcnt(2)
	v_lshlrev_b32_e32 v44, 16, v34
	v_fma_f32 v77, v22, v120, v77
	v_add_f32_e32 v76, v76, v77
	v_mul_f32_e32 v61, v76, v61
	v_mov_b32_e32 v76, v18
	v_mov_b32_e32 v77, v22
	v_pk_mul_f32 v[40:41], v[76:77], v[40:41]
	v_mov_b32_e32 v22, v19
	v_fma_f32 v14, v14, v120, v41
	v_add_f32_e32 v14, v40, v14
	v_and_b32_e32 v41, 0xffff0000, v26
	v_and_b32_e32 v40, 0xffff0000, v30
	v_pk_mul_f32 v[18:19], v[22:23], v[40:41]
	v_pk_mov_b32 v[74:75], v[40:41], v[74:75] op_sel:[1,0]
	v_fma_f32 v15, v15, v84, v19
	v_pk_mul_f32 v[74:75], v[106:107], v[74:75]
	v_add_f32_e32 v15, v18, v15
	v_lshlrev_b32_e32 v19, 16, v27
	v_lshlrev_b32_e32 v18, 16, v31
	v_mul_f32_e32 v44, v14, v44
	v_fma_f32 v14, v23, v84, v75
	v_pk_mov_b32 v[22:23], v[18:19], v[72:73] op_sel:[1,0]
	v_and_b32_e32 v34, 0xffff0000, v34
	v_pk_mul_f32 v[22:23], v[108:109], v[22:23]
	v_mul_f32_e32 v26, v15, v34
	v_fma_f32 v23, v24, v86, v23
	v_add_f32_e32 v22, v22, v23
	v_mul_f32_e32 v30, v22, v73
	v_mov_b32_e32 v22, v20
	v_mov_b32_e32 v23, v24
	v_pk_mul_f32 v[18:19], v[22:23], v[18:19]
	v_mov_b32_e32 v24, v21
	v_fma_f32 v16, v16, v86, v19
	v_add_f32_e32 v16, v18, v16
	v_and_b32_e32 v19, 0xffff0000, v27
	v_and_b32_e32 v18, 0xffff0000, v31
	v_pk_mov_b32 v[22:23], v[18:19], v[68:69] op_sel:[1,0]
	v_pk_mul_f32 v[18:19], v[24:25], v[18:19]
	v_lshlrev_b32_e32 v15, 16, v35
	v_fma_f32 v17, v17, v88, v19
	v_mul_f32_e32 v20, v16, v15
	v_and_b32_e32 v16, 0xffff0000, v35
	v_add_f32_e32 v17, v18, v17
	v_and_b32_e32 v65, 0xffff0000, v100
	v_mul_f32_e32 v21, v17, v16
	v_lshlrev_b32_e32 v17, 16, v28
	v_lshlrev_b32_e32 v16, 16, v32
	v_pk_mov_b32 v[18:19], v[16:17], v[64:65] op_sel:[1,0]
	v_lshlrev_b32_e32 v83, 16, v102
	v_pk_mul_f32 v[18:19], v[80:81], v[18:19]
	v_pk_mul_f32 v[22:23], v[110:111], v[22:23]
	v_fma_f32 v19, v10, v90, v19
	v_add_f32_e32 v18, v18, v19
	v_fma_f32 v15, v25, v88, v23
	v_mul_f32_e32 v23, v18, v83
	v_mov_b32_e32 v18, v6
	v_mov_b32_e32 v19, v10
	v_pk_mul_f32 v[16:17], v[18:19], v[16:17]
	v_and_b32_e32 v19, 0xffff0000, v28
	v_fma_f32 v2, v2, v90, v17
	v_and_b32_e32 v18, 0xffff0000, v32
	v_add_f32_e32 v2, v16, v2
	v_pk_mov_b32 v[16:17], v[18:19], v[62:63] op_sel:[1,0]
	v_and_b32_e32 v82, 0xffff0000, v101
	v_pk_mul_f32 v[16:17], v[78:79], v[16:17]
	v_and_b32_e32 v85, 0xffff0000, v102
	v_fma_f32 v6, v11, v92, v17
	v_add_f32_e32 v14, v74, v14
	v_add_f32_e32 v15, v22, v15
	v_add_f32_e32 v6, v16, v6
	v_mul_f32_e32 v14, v14, v65
	v_mul_f32_e32 v15, v15, v82
	v_mul_f32_e32 v6, v6, v85
	v_mov_b32_e32 v10, v7
	v_cvt_pk_bf16_f32 v14, v61, v14
	v_cvt_pk_bf16_f32 v15, v30, v15
	v_cvt_pk_bf16_f32 v16, v23, v6
	v_pk_mul_f32 v[6:7], v[10:11], v[18:19]
	v_lshlrev_b32_e32 v22, 16, v36
	v_fma_f32 v3, v3, v92, v7
	v_mul_f32_e32 v22, v2, v22
	v_and_b32_e32 v2, 0xffff0000, v36
	v_add_f32_e32 v3, v6, v3
	v_mul_f32_e32 v10, v3, v2
	v_lshlrev_b32_e32 v3, 16, v29
	v_lshlrev_b32_e32 v2, 16, v33
	v_pk_mov_b32 v[6:7], v[2:3], v[60:61] op_sel:[1,0]
	v_lshlrev_b32_e32 v87, 16, v103
	v_pk_mul_f32 v[6:7], v[70:71], v[6:7]
	v_lshlrev_b32_e32 v11, 16, v37
	v_fma_f32 v7, v12, v96, v7
	v_add_f32_e32 v6, v6, v7
	v_mul_f32_e32 v17, v6, v87
	v_mov_b32_e32 v6, v8
	v_mov_b32_e32 v7, v12
	v_pk_mul_f32 v[2:3], v[6:7], v[2:3]
	v_and_b32_e32 v7, 0xffff0000, v29
	v_fma_f32 v3, v4, v96, v3
	v_add_f32_e32 v2, v2, v3
	v_and_b32_e32 v6, 0xffff0000, v33
	v_mul_f32_e32 v8, v2, v11
	v_pk_mov_b32 v[2:3], v[6:7], v[58:59] op_sel:[1,0]
	v_lshl_add_u64 v[38:39], v[38:39], 0, v[56:57]
	v_pk_mul_f32 v[2:3], v[66:67], v[2:3]
	v_mov_b32_e32 v12, v9
	v_fma_f32 v3, v13, v94, v3
	v_add_f32_e32 v2, v2, v3
	v_mul_f32_e32 v2, v2, v89
	v_cvt_pk_bf16_f32 v17, v17, v2
	v_add_co_u32_e32 v2, vcc, s6, v38
	v_pk_mul_f32 v[6:7], v[12:13], v[6:7]
	s_nop 0
	v_addc_co_u32_e32 v3, vcc, 0, v39, vcc
	global_store_dwordx4 v[2:3], v[14:17], off
	v_cvt_pk_bf16_f32 v2, v44, v26
	v_fma_f32 v5, v5, v94, v7
	v_lshlrev_b32_e32 v44, 13, v123
	v_add_f32_e32 v5, v6, v5
	v_lshl_add_u64 v[6:7], s[60:61], 0, v[44:45]
	v_lshl_add_u64 v[6:7], v[6:7], 0, v[56:57]
	v_add_co_u32_e32 v6, vcc, 0x1000, v6
	v_and_b32_e32 v11, 0xffff0000, v37
	s_nop 0
	v_addc_co_u32_e32 v7, vcc, 0, v7, vcc
	v_cmp_lt_u64_e32 vcc, s[52:53], v[42:43]
	v_mul_f32_e32 v5, v5, v11
	s_or_b64 s[10:11], vcc, s[10:11]
	v_cvt_pk_bf16_f32 v3, v20, v21
	v_cvt_pk_bf16_f32 v4, v22, v10
	v_cvt_pk_bf16_f32 v5, v8, v5
	global_store_dwordx4 v[6:7], v[2:5], off
	s_andn2_b64 exec, exec, s[10:11]
	s_cbranch_execz .LBB0_660
.LBB0_656:
	v_lshrrev_b32_e32 v30, 6, v42
	v_and_b32_e32 v82, 0x3ffc, v30
	v_and_b32_e32 v2, 0x3ff00, v42
	v_cmp_ne_u32_e64 s[0:1], 0, v2
	v_mul_u32_u24_e32 v44, 0x1080, v82
	v_mov_b32_e32 v26, 0
	v_mov_b32_e32 v27, 0
	v_mov_b32_e32 v28, 0
	v_mov_b32_e32 v29, 0
	s_and_saveexec_b64 s[14:15], s[0:1]
	s_cbranch_execz .LBB0_658
	v_lshl_add_u64 v[2:3], v[46:47], 0, v[44:45]
	v_add_co_u32_e32 v2, vcc, 0xffffdf00, v2
	s_nop 1
	v_addc_co_u32_e32 v3, vcc, -1, v3, vcc
	global_load_dwordx4 v[26:29], v[2:3], off
.LBB0_658:
	s_or_b64 exec, exec, s[14:15]
	v_mov_b32_e32 v38, 0
	v_mov_b32_e32 v39, 0
	v_mov_b32_e32 v40, 0
	v_mov_b32_e32 v41, 0
	s_and_saveexec_b64 s[14:15], s[0:1]
	s_cbranch_execz .LBB0_655
	v_lshl_add_u64 v[2:3], v[46:47], 0, v[44:45]
	v_add_co_u32_e32 v2, vcc, 0xffffef80, v2
	s_nop 1
	v_addc_co_u32_e32 v3, vcc, -1, v3, vcc
	global_load_dwordx4 v[38:41], v[2:3], off
	s_branch .LBB0_655
